# norm_rows mode 1 (3 copies): updated rows staged in LDS per 8-row slab, each wave then stores whole K-tile slabs (1 KiB contiguous per store) instead of eight scattered 128 B pieces
# speedup vs baseline: 1.0106x; 1.0007x over previous
; __device__ __forceinline__ size_t xoff(int row, int col) { return ((size_t)((row >> 8) * 32 + (col >> 6)) * 256 + (row & 255)) * 64 + (col & 63); }
; __device__ __forceinline__ void unpack8(u32x4 w, f32x4& v0, f32x4& v1) { v0 = (f32x4){bflo(w.x), bfhi(w.x), bflo(w.y), bfhi(w.y)}; v1 = (f32x4){bflo(w.z), bfhi(w.z), bflo(w.w), bfhi(w.w)}; }
; __device__ void norm_rows(const Params& p, int mode, float scale, const float* gpost) {
;     ...
;             f32x4 yv[8]; float ss = 0.f; u32x4 xw[4], yw[4]; f32x4 gq[8];
; #pragma unroll
;             for (int c = 0; c < 4; ++c) { xw[c] = *(const u32x4*)(X + xoff(row, (c * 64 + lane) * 8)); yw[c] = *(const u32x4*)(Y + (size_t)row * DM + (c * 64 + lane) * 8); }
; #pragma unroll
;             for (int c = 0; c < 4; ++c) { gq[2 * c] = *(const f32x4*)(gpost + (c * 64 + lane) * 8); gq[2 * c + 1] = *(const f32x4*)(gpost + (c * 64 + lane) * 8 + 4); }
;             asm volatile("" ::: "memory");
; #pragma unroll
;             for (int c = 0; c < 4; ++c) { unpack8(xw[c], xv[2 * c], xv[2 * c + 1]); unpack8(yw[c], yv[2 * c], yv[2 * c + 1]); }
; #pragma unroll
;             for (int c = 0; c < 8; ++c) ss += yv[c][0] * yv[c][0] + yv[c][1] * yv[c][1] + yv[c][2] * yv[c][2] + yv[c][3] * yv[c][3];
;             ss = wave_sum(ss);
;             const float rs = rsqrtf(ss * (1.0f / DM) + RMS_EPS) * scale;
.LBB0_27:
	v_ashrrev_i32_e32 v47, 31, v46
	s_waitcnt lgkmcnt(0)
	v_lshlrev_b64 v[2:3], 12, v[46:47]
	v_lshl_add_u64 v[2:3], v[58:59], 0, v[2:3]
	global_load_dwordx4 v[74:77], v[2:3], off offset:1024
	global_load_dwordx4 v[92:95], v[2:3], off offset:2048
	v_ashrrev_i32_e32 v0, 3, v46
	v_and_b32_e32 v39, 0xffffffe0, v0
	v_and_b32_e32 v4, 0x3fc0, v90
	v_or_b32_e32 v62, v39, v86
	v_lshlrev_b32_e32 v0, 1, v4
	v_ashrrev_i32_e32 v63, 31, v62
	v_lshl_add_u64 v[60:61], v[48:49], 0, v[0:1]
	v_lshlrev_b64 v[4:5], 15, v[62:63]
	v_lshl_add_u64 v[64:65], v[60:61], 0, v[4:5]
	global_load_dwordx4 v[42:45], v[2:3], off offset:3072
	global_load_dwordx4 v[34:37], v[64:65], off
	global_load_dwordx4 v[96:99], v[2:3], off
	global_load_dwordx4 v[26:29], v[50:51], off offset:16
	global_load_dwordx4 v[30:33], v[50:51], off
	global_load_dwordx4 v[18:21], v[52:53], off offset:16
	global_load_dwordx4 v[22:25], v[52:53], off
	global_load_dwordx4 v[10:13], v[54:55], off offset:16
	global_load_dwordx4 v[14:17], v[54:55], off
	global_load_dwordx4 v[2:5], v[56:57], off offset:16
	global_load_dwordx4 v[6:9], v[56:57], off
	v_or_b32_e32 v38, v39, v87
	v_or_b32_e32 v40, v39, v88
	v_or_b32_e32 v66, v39, v89
	v_ashrrev_i32_e32 v39, 31, v38
	v_lshlrev_b64 v[38:39], 15, v[38:39]
	v_ashrrev_i32_e32 v41, 31, v40
	v_lshl_add_u64 v[38:39], v[60:61], 0, v[38:39]
	v_ashrrev_i32_e32 v67, 31, v66
	global_load_dwordx4 v[100:103], v[38:39], off
	v_lshlrev_b64 v[38:39], 15, v[40:41]
	v_lshlrev_b64 v[40:41], 15, v[66:67]
	v_lshl_add_u64 v[38:39], v[60:61], 0, v[38:39]
	v_lshl_add_u64 v[40:41], v[60:61], 0, v[40:41]
	global_load_dwordx4 v[104:107], v[38:39], off
	s_nop 0
	global_load_dwordx4 v[38:41], v[40:41], off
	s_mov_b32 s0, 0x800000
	s_waitcnt vmcnt(15)
	v_and_b32_e32 v73, 0xffff0000, v74
	v_lshlrev_b32_e32 v72, 16, v74
	v_and_b32_e32 v69, 0xffff0000, v76
	v_mul_f32_e32 v0, v73, v73
	s_waitcnt vmcnt(11)
	v_and_b32_e32 v115, 0xffff0000, v96
	v_and_b32_e32 v117, 0xffff0000, v98
	v_lshlrev_b32_e32 v114, 16, v96
	v_lshlrev_b32_e32 v116, 16, v98
	v_mul_f32_e32 v91, v115, v115
	v_mul_f32_e32 v113, v117, v117
	v_lshlrev_b32_e32 v96, 16, v97
	v_lshlrev_b32_e32 v98, 16, v99
	v_fmac_f32_e32 v91, v114, v114
	v_fmac_f32_e32 v113, v116, v116
	v_lshlrev_b32_e32 v70, 16, v75
	v_lshlrev_b32_e32 v68, 16, v76
	v_and_b32_e32 v79, 0xffff0000, v92
	v_and_b32_e32 v78, 0xffff0000, v94
	v_mul_f32_e32 v63, v69, v69
	v_fmac_f32_e32 v0, v72, v72
	v_and_b32_e32 v97, 0xffff0000, v97
	v_and_b32_e32 v99, 0xffff0000, v99
	v_fmac_f32_e32 v91, v96, v96
	v_fmac_f32_e32 v113, v98, v98
	v_and_b32_e32 v71, 0xffff0000, v75
	v_lshlrev_b32_e32 v66, 16, v77
	v_lshlrev_b32_e32 v75, 16, v92
	v_lshlrev_b32_e32 v74, 16, v94
	v_pk_mul_f32 v[108:109], v[78:79], v[78:79]
	v_fmac_f32_e32 v63, v68, v68
	v_fmac_f32_e32 v0, v70, v70
	v_fmac_f32_e32 v91, v97, v97
	v_fmac_f32_e32 v113, v99, v99
	v_and_b32_e32 v67, 0xffff0000, v77
	v_lshlrev_b32_e32 v77, 16, v93
	v_lshlrev_b32_e32 v76, 16, v95
	v_pk_fma_f32 v[108:109], v[74:75], v[74:75], v[108:109]
	v_fmac_f32_e32 v63, v66, v66
	v_fmac_f32_e32 v0, v71, v71
	v_add_f32_e32 v91, v91, v113
	v_and_b32_e32 v93, 0xffff0000, v93
	v_and_b32_e32 v92, 0xffff0000, v95
	v_pk_fma_f32 v[108:109], v[76:77], v[76:77], v[108:109]
	v_fmac_f32_e32 v63, v67, v67
	v_add_f32_e32 v0, v91, v0
	v_pk_fma_f32 v[108:109], v[92:93], v[92:93], v[108:109]
	v_add_f32_e32 v0, v63, v0
	v_add_f32_e32 v0, v0, v109
	v_add_f32_e32 v0, v108, v0
	v_and_b32_e32 v109, 0xffff0000, v42
	v_and_b32_e32 v108, 0xffff0000, v44
	v_lshlrev_b32_e32 v95, 16, v42
	v_lshlrev_b32_e32 v94, 16, v44
	v_lshlrev_b32_e32 v118, 16, v45
	v_and_b32_e32 v42, 0xffff0000, v45
	v_pk_mul_f32 v[44:45], v[108:109], v[108:109]
	v_lshlrev_b32_e32 v119, 16, v43
	v_pk_fma_f32 v[44:45], v[94:95], v[94:95], v[44:45]
	v_and_b32_e32 v43, 0xffff0000, v43
	v_pk_fma_f32 v[44:45], v[118:119], v[118:119], v[44:45]
	v_lshlrev_b32_e32 v110, 16, v34
	v_pk_fma_f32 v[44:45], v[42:43], v[42:43], v[44:45]
	v_and_b32_e32 v111, 0xffff0000, v34
	v_add_f32_e32 v0, v0, v45
	v_add_f32_e32 v0, v44, v0
	ds_bpermute_b32 v45, v80, v0
	v_lshlrev_b32_e32 v34, 16, v35
	v_and_b32_e32 v35, 0xffff0000, v35
	s_waitcnt vmcnt(9)
	v_pk_mul_f32 v[32:33], v[32:33], v[96:97]
	v_lshlrev_b32_e32 v112, 16, v36
	s_waitcnt lgkmcnt(0)
	v_add_f32_e32 v0, v0, v45
	ds_bpermute_b32 v63, v81, v0
	v_and_b32_e32 v113, 0xffff0000, v36
	v_pk_mul_f32 v[30:31], v[30:31], v[114:115]
	v_pk_mul_f32 v[26:27], v[26:27], v[116:117]
	v_lshlrev_b32_e32 v36, 16, v37
	s_waitcnt lgkmcnt(0)
	v_add_f32_e32 v0, v0, v63
	ds_bpermute_b32 v63, v82, v0
	v_and_b32_e32 v37, 0xffff0000, v37
	s_waitcnt vmcnt(2)
	v_lshlrev_b32_e32 v44, 16, v100
	v_and_b32_e32 v45, 0xffff0000, v100
	v_lshlrev_b32_e32 v100, 16, v101
	s_waitcnt lgkmcnt(0)
	v_add_f32_e32 v0, v0, v63
	ds_bpermute_b32 v63, v83, v0
	v_and_b32_e32 v101, 0xffff0000, v101
	v_lshlrev_b32_e32 v120, 16, v102
	v_and_b32_e32 v121, 0xffff0000, v102
	v_lshlrev_b32_e32 v102, 16, v103
	s_waitcnt lgkmcnt(0)
	v_add_f32_e32 v0, v0, v63
	ds_bpermute_b32 v63, v84, v0
	v_and_b32_e32 v103, 0xffff0000, v103
	s_waitcnt vmcnt(1)
	v_lshlrev_b32_e32 v122, 16, v104
	v_and_b32_e32 v123, 0xffff0000, v104
	v_lshlrev_b32_e32 v104, 16, v105
	s_waitcnt lgkmcnt(0)
	v_add_f32_e32 v0, v0, v63
	ds_bpermute_b32 v63, v85, v0
	v_and_b32_e32 v105, 0xffff0000, v105
	v_lshlrev_b32_e32 v124, 16, v106
	v_and_b32_e32 v125, 0xffff0000, v106
	v_lshlrev_b32_e32 v106, 16, v107
	s_waitcnt lgkmcnt(0)
	v_add_f32_e32 v0, v0, v63
	v_fmamk_f32 v0, v0, 0x3a000000, v223
	v_mul_f32_e32 v63, 0x4b800000, v0
	v_cmp_gt_f32_e64 s[36:37], s0, v0
	v_and_b32_e32 v107, 0xffff0000, v107
	s_waitcnt vmcnt(0)
; __device__ __forceinline__ size_t xoff(int row, int col) { return ((size_t)((row >> 8) * 32 + (col >> 6)) * 256 + (row & 255)) * 64 + (col & 63); }
; __device__ __forceinline__ u32x4 pack8(f32x4 v0, f32x4 v1) { u32x4 w; w.x = cvt_pk_bf16(v0[0], v0[1]); w.y = cvt_pk_bf16(v0[2], v0[3]); w.z = cvt_pk_bf16(v1[0], v1[1]); w.w = cvt_pk_bf16(v1[2], v1[3]); return w; }
; __device__ void norm_rows(const Params& p, int mode, float scale, const float* gpost) {
;     ...
;             for (int c = 0; c < 4; ++c) { xv[2 * c] += yv[2 * c] * gq[2 * c] * rs; xv[2 * c + 1] += yv[2 * c + 1] * gq[2 * c + 1] * rs; }
;         }
;         if (mode == 2) {
; #pragma unroll
;             for (int c = 0; c < 4; ++c) { *(f32x4*)(p.out + (size_t)row * DM + (c * 64 + lane) * 8) = xv[2 * c]; *(f32x4*)(p.out + (size_t)row * DM + (c * 64 + lane) * 8 + 4) = xv[2 * c + 1]; }
;         } else {
;             float ss = 0.f;
; #pragma unroll
;             for (int c = 0; c < 8; ++c) ss += xv[c][0] * xv[c][0] + xv[c][1] * xv[c][1] + xv[c][2] * xv[c][2] + xv[c][3] * xv[c][3];
;             ss = wave_sum(ss);
; #pragma unroll
;             for (int c = 0; c < 4; ++c) *(u32x4*)(X + xoff(row, (c * 64 + lane) * 8)) = pack8(xv[2 * c], xv[2 * c + 1]);
;             if (lane == 0) RS[row] = rsqrtf(ss * (1.0f / DM) + RMS_EPS);
	v_lshlrev_b32_e32 v126, 16, v38
	v_cndmask_b32_e64 v0, v0, v63, s[36:37]
	v_rsq_f32_e32 v0, v0
	v_and_b32_e32 v127, 0xffff0000, v38
	v_lshlrev_b32_e32 v38, 16, v39
	v_and_b32_e32 v39, 0xffff0000, v39
	v_mul_f32_e32 v63, 0x45800000, v0
	v_cndmask_b32_e64 v0, v0, v63, s[36:37]
	v_pk_fma_f32 v[32:33], v[32:33], v[0:1], v[34:35] op_sel_hi:[1,0,1]
	v_mov_b32_e32 v34, v75
	v_mov_b32_e32 v35, v79
	v_pk_mul_f32 v[14:15], v[14:15], v[34:35]
	v_mov_b32_e32 v34, v77
	v_mov_b32_e32 v35, v93
	v_pk_mul_f32 v[16:17], v[16:17], v[34:35]
	v_mov_b32_e32 v34, v95
	v_mov_b32_e32 v35, v109
	v_mov_b32_e32 v75, v78
	v_mov_b32_e32 v77, v92
	v_pk_mul_f32 v[6:7], v[6:7], v[34:35]
	v_mov_b32_e32 v34, v119
	v_mov_b32_e32 v35, v43
	v_mov_b32_e32 v95, v108
	v_mov_b32_e32 v119, v42
	v_lshlrev_b32_e32 v128, 16, v40
	v_and_b32_e32 v129, 0xffff0000, v40
	v_lshlrev_b32_e32 v40, 16, v41
	v_and_b32_e32 v41, 0xffff0000, v41
	v_pk_fma_f32 v[30:31], v[30:31], v[0:1], v[110:111] op_sel_hi:[1,0,1]
	v_pk_mul_f32 v[28:29], v[28:29], v[98:99]
	v_pk_fma_f32 v[26:27], v[26:27], v[0:1], v[112:113] op_sel_hi:[1,0,1]
	v_pk_mul_f32 v[22:23], v[22:23], v[72:73]
	v_pk_mul_f32 v[24:25], v[24:25], v[70:71]
	v_pk_mul_f32 v[18:19], v[18:19], v[68:69]
	v_pk_mul_f32 v[20:21], v[20:21], v[66:67]
	v_pk_mul_f32 v[10:11], v[10:11], v[74:75]
	v_pk_mul_f32 v[12:13], v[12:13], v[76:77]
	v_pk_mul_f32 v[8:9], v[8:9], v[34:35]
	v_pk_mul_f32 v[2:3], v[2:3], v[94:95]
	v_pk_mul_f32 v[4:5], v[4:5], v[118:119]
	v_pk_fma_f32 v[28:29], v[28:29], v[0:1], v[36:37] op_sel_hi:[1,0,1]
	v_pk_fma_f32 v[24:25], v[24:25], v[0:1], v[100:101] op_sel_hi:[1,0,1]
	v_pk_fma_f32 v[22:23], v[22:23], v[0:1], v[44:45] op_sel_hi:[1,0,1]
	v_pk_fma_f32 v[20:21], v[20:21], v[0:1], v[102:103] op_sel_hi:[1,0,1]
	v_pk_fma_f32 v[18:19], v[18:19], v[0:1], v[120:121] op_sel_hi:[1,0,1]
	v_pk_fma_f32 v[16:17], v[16:17], v[0:1], v[104:105] op_sel_hi:[1,0,1]
	v_pk_fma_f32 v[14:15], v[14:15], v[0:1], v[122:123] op_sel_hi:[1,0,1]
	v_pk_fma_f32 v[12:13], v[12:13], v[0:1], v[106:107] op_sel_hi:[1,0,1]
	v_pk_fma_f32 v[10:11], v[10:11], v[0:1], v[124:125] op_sel_hi:[1,0,1]
	v_pk_fma_f32 v[8:9], v[8:9], v[0:1], v[38:39] op_sel_hi:[1,0,1]
	v_pk_fma_f32 v[34:35], v[6:7], v[0:1], v[126:127] op_sel_hi:[1,0,1]
	v_pk_fma_f32 v[36:37], v[4:5], v[0:1], v[40:41] op_sel_hi:[1,0,1]
	v_pk_fma_f32 v[38:39], v[2:3], v[0:1], v[128:129] op_sel_hi:[1,0,1]
	v_mul_f32_e32 v0, v31, v31
	v_mul_f32_e32 v2, v27, v27
	v_fmac_f32_e32 v0, v30, v30
	v_fmac_f32_e32 v2, v26, v26
	v_fmac_f32_e32 v0, v32, v32
	v_fmac_f32_e32 v2, v28, v28
	v_fmac_f32_e32 v0, v33, v33
	v_fmac_f32_e32 v2, v29, v29
	v_add_f32_e32 v0, v0, v2
	v_mul_f32_e32 v2, v23, v23
	v_fmac_f32_e32 v2, v22, v22
	v_fmac_f32_e32 v2, v24, v24
	v_fmac_f32_e32 v2, v25, v25
	v_add_f32_e32 v0, v2, v0
	v_mul_f32_e32 v2, v19, v19
	v_fmac_f32_e32 v2, v18, v18
	v_fmac_f32_e32 v2, v20, v20
	v_fmac_f32_e32 v2, v21, v21
	v_add_f32_e32 v0, v2, v0
	v_mul_f32_e32 v2, v15, v15
	v_fmac_f32_e32 v2, v14, v14
	v_fmac_f32_e32 v2, v16, v16
	v_fmac_f32_e32 v2, v17, v17
	v_add_f32_e32 v0, v2, v0
	v_mul_f32_e32 v2, v11, v11
	v_fmac_f32_e32 v2, v10, v10
	v_fmac_f32_e32 v2, v12, v12
	v_fmac_f32_e32 v2, v13, v13
	v_add_f32_e32 v0, v2, v0
	v_mul_f32_e32 v2, v35, v35
	v_fmac_f32_e32 v2, v34, v34
	v_fmac_f32_e32 v2, v8, v8
	v_fmac_f32_e32 v2, v9, v9
	v_add_f32_e32 v0, v2, v0
	v_mul_f32_e32 v2, v39, v39
	v_fmac_f32_e32 v2, v38, v38
	v_fmac_f32_e32 v2, v36, v36
	v_fmac_f32_e32 v2, v37, v37
	v_add_f32_e32 v0, v2, v0
	ds_bpermute_b32 v2, v80, v0
	v_cvt_pk_bf16_f32 v6, v26, v27
	v_cvt_pk_bf16_f32 v4, v30, v31
	v_cvt_pk_bf16_f32 v5, v32, v33
	v_cvt_pk_bf16_f32 v7, v28, v29
	s_waitcnt lgkmcnt(0)
	v_add_f32_e32 v0, v0, v2
	ds_bpermute_b32 v2, v81, v0
	v_lshrrev_b32_e32 v204, 6, v229
	v_mul_u32_u24_e32 v205, 0x1010, v204
	v_lshl_add_u32 v205, v228, 4, v205
	ds_write_b128 v205, v[4:7]
	s_waitcnt lgkmcnt(0)
	v_add_f32_e32 v0, v0, v2
	ds_bpermute_b32 v2, v82, v0
	v_cvt_pk_bf16_f32 v6, v18, v19
	v_or_b32_e32 v18, 8, v62
	v_ashrrev_i32_e32 v19, 31, v18
	v_lshlrev_b64 v[18:19], 15, v[18:19]
	s_waitcnt lgkmcnt(0)
	v_add_f32_e32 v0, v0, v2
	ds_bpermute_b32 v2, v83, v0
	v_lshl_add_u64 v[18:19], v[60:61], 0, v[18:19]
	v_cvt_pk_bf16_f32 v4, v22, v23
	v_cvt_pk_bf16_f32 v5, v24, v25
	v_cvt_pk_bf16_f32 v7, v20, v21
	s_waitcnt lgkmcnt(0)
	v_add_f32_e32 v0, v0, v2
	ds_bpermute_b32 v2, v84, v0
	ds_write_b128 v205, v[4:7] offset:1024
	s_waitcnt lgkmcnt(0)
	v_add_f32_e32 v0, v0, v2
	v_cvt_pk_bf16_f32 v6, v10, v11
	v_or_b32_e32 v10, 16, v62
	v_ashrrev_i32_e32 v11, 31, v10
	v_lshlrev_b64 v[10:11], 15, v[10:11]
	ds_bpermute_b32 v2, v85, v0
	v_cvt_pk_bf16_f32 v5, v16, v17
	v_lshl_add_u64 v[10:11], v[60:61], 0, v[10:11]
	v_cvt_pk_bf16_f32 v4, v14, v15
	v_cvt_pk_bf16_f32 v7, v12, v13
	ds_write_b128 v205, v[4:7] offset:2048
	s_nop 1
	v_cvt_pk_bf16_f32 v5, v8, v9
	v_or_b32_e32 v8, 24, v62
	v_ashrrev_i32_e32 v9, 31, v8
	v_lshlrev_b64 v[8:9], 15, v[8:9]
	v_lshl_add_u64 v[8:9], v[60:61], 0, v[8:9]
	v_cvt_pk_bf16_f32 v4, v34, v35
	v_cvt_pk_bf16_f32 v6, v38, v39
	v_cvt_pk_bf16_f32 v7, v36, v37
	ds_write_b128 v205, v[4:7] offset:3072
	v_readlane_b32 s2, v252, 6
	v_readlane_b32 s3, v252, 7
	v_lshrrev_b32_e32 v206, 3, v228
	v_mul_u32_u24_e32 v206, 0x1010, v206
	v_and_b32_e32 v207, 7, v228
	v_lshl_add_u32 v206, v204, 9, v206
	v_lshl_add_u32 v206, v207, 4, v206
	s_waitcnt lgkmcnt(0)
	s_barrier
	ds_read_b128 v[184:187], v206
	ds_read_b128 v[188:191], v206 offset:128
	ds_read_b128 v[196:199], v206 offset:256
	ds_read_b128 v[200:203], v206 offset:384
	v_lshrrev_b32_e32 v207, 8, v46
	v_lshlrev_b32_e32 v207, 5, v207
	v_lshl_add_u32 v207, v204, 2, v207
	v_lshlrev_b32_e32 v207, 15, v207
	v_and_b32_e32 v208, 0xf8, v46
	v_lshl_add_u32 v207, v208, 7, v207
	v_lshl_add_u32 v207, v228, 4, v207
	v_add_u32_e32 v208, 0x8000, v207
	v_add_u32_e32 v209, 0x10000, v207
	v_add_u32_e32 v210, 0x18000, v207
	s_waitcnt lgkmcnt(0)
	global_store_dwordx4 v207, v[184:187], s[2:3]
	global_store_dwordx4 v208, v[188:191], s[2:3]
	global_store_dwordx4 v209, v[196:199], s[2:3]
	global_store_dwordx4 v210, v[200:203], s[2:3]
	s_barrier
	s_and_saveexec_b64 s[0:1], vcc
	s_cbranch_execz .LBB0_26
	s_waitcnt lgkmcnt(0)
	v_add_f32_e32 v0, v0, v2
	v_fmamk_f32 v0, v0, 0x3a000000, v223
	s_mov_b32 s2, 0x800000
	v_mul_f32_e32 v2, 0x4b800000, v0
	v_cmp_gt_f32_e64 s[36:37], s2, v0
	v_readlane_b32 s2, v254, 22
	v_readlane_b32 s3, v254, 23
	v_cndmask_b32_e64 v0, v0, v2, s[36:37]
	v_rsq_f32_e32 v0, v0
	s_nop 0
	v_mul_f32_e32 v2, 0x45800000, v0
	v_cndmask_b32_e64 v0, v0, v2, s[36:37]
	v_lshl_add_u64 v[2:3], v[46:47], 2, s[2:3]
	global_store_dword v[2:3], v0, off
	s_branch .LBB0_26

; __device__ __forceinline__ size_t xoff(int row, int col) { return ((size_t)((row >> 8) * 32 + (col >> 6)) * 256 + (row & 255)) * 64 + (col & 63); }
; __device__ __forceinline__ void unpack8(u32x4 w, f32x4& v0, f32x4& v1) { v0 = (f32x4){bflo(w.x), bfhi(w.x), bflo(w.y), bfhi(w.y)}; v1 = (f32x4){bflo(w.z), bfhi(w.z), bflo(w.w), bfhi(w.w)}; }
; __device__ void norm_rows(const Params& p, int mode, float scale, const float* gpost) {
;     ...
;             f32x4 yv[8]; float ss = 0.f; u32x4 xw[4], yw[4]; f32x4 gq[8];
; #pragma unroll
;             for (int c = 0; c < 4; ++c) { xw[c] = *(const u32x4*)(X + xoff(row, (c * 64 + lane) * 8)); yw[c] = *(const u32x4*)(Y + (size_t)row * DM + (c * 64 + lane) * 8); }
; #pragma unroll
;             for (int c = 0; c < 4; ++c) { gq[2 * c] = *(const f32x4*)(gpost + (c * 64 + lane) * 8); gq[2 * c + 1] = *(const f32x4*)(gpost + (c * 64 + lane) * 8 + 4); }
;             asm volatile("" ::: "memory");
; #pragma unroll
;             for (int c = 0; c < 4; ++c) { unpack8(xw[c], xv[2 * c], xv[2 * c + 1]); unpack8(yw[c], yv[2 * c], yv[2 * c + 1]); }
; #pragma unroll
;             for (int c = 0; c < 8; ++c) ss += yv[c][0] * yv[c][0] + yv[c][1] * yv[c][1] + yv[c][2] * yv[c][2] + yv[c][3] * yv[c][3];
;             ss = wave_sum(ss);
;             const float rs = rsqrtf(ss * (1.0f / DM) + RMS_EPS) * scale;
.LBB0_787:
	v_ashrrev_i32_e32 v47, 31, v46
	s_waitcnt lgkmcnt(0)
	v_lshlrev_b64 v[2:3], 12, v[46:47]
	v_lshl_add_u64 v[2:3], v[58:59], 0, v[2:3]
	global_load_dwordx4 v[74:77], v[2:3], off offset:1024
	global_load_dwordx4 v[94:97], v[2:3], off offset:2048
	v_ashrrev_i32_e32 v0, 3, v46
	v_and_b32_e32 v39, 0xffffffe0, v0
	v_and_b32_e32 v4, 0x3fc0, v92
	v_or_b32_e32 v62, v39, v88
	v_lshlrev_b32_e32 v0, 1, v4
	v_ashrrev_i32_e32 v63, 31, v62
	v_lshl_add_u64 v[60:61], v[48:49], 0, v[0:1]
	v_lshlrev_b64 v[4:5], 15, v[62:63]
	v_lshl_add_u64 v[64:65], v[60:61], 0, v[4:5]
	global_load_dwordx4 v[42:45], v[2:3], off offset:3072
	global_load_dwordx4 v[34:37], v[64:65], off
	global_load_dwordx4 v[98:101], v[2:3], off
	global_load_dwordx4 v[26:29], v[50:51], off offset:16
	global_load_dwordx4 v[30:33], v[50:51], off
	global_load_dwordx4 v[18:21], v[52:53], off offset:16
	global_load_dwordx4 v[22:25], v[52:53], off
	global_load_dwordx4 v[10:13], v[54:55], off offset:16
	global_load_dwordx4 v[14:17], v[54:55], off
	global_load_dwordx4 v[2:5], v[56:57], off offset:16
	global_load_dwordx4 v[6:9], v[56:57], off
	v_or_b32_e32 v38, v39, v89
	v_or_b32_e32 v40, v39, v90
	v_or_b32_e32 v66, v39, v91
	v_ashrrev_i32_e32 v39, 31, v38
	v_lshlrev_b64 v[38:39], 15, v[38:39]
	v_ashrrev_i32_e32 v41, 31, v40
	v_lshl_add_u64 v[38:39], v[60:61], 0, v[38:39]
	v_ashrrev_i32_e32 v67, 31, v66
	global_load_dwordx4 v[102:105], v[38:39], off
	v_lshlrev_b64 v[38:39], 15, v[40:41]
	v_lshlrev_b64 v[40:41], 15, v[66:67]
	v_lshl_add_u64 v[38:39], v[60:61], 0, v[38:39]
	v_lshl_add_u64 v[40:41], v[60:61], 0, v[40:41]
	global_load_dwordx4 v[106:109], v[38:39], off
	s_nop 0
	global_load_dwordx4 v[38:41], v[40:41], off
	s_mov_b32 s0, 0x800000
	s_waitcnt vmcnt(15)
	v_and_b32_e32 v73, 0xffff0000, v74
	v_lshlrev_b32_e32 v72, 16, v74
	v_and_b32_e32 v69, 0xffff0000, v76
	v_mul_f32_e32 v0, v73, v73
	s_waitcnt vmcnt(11)
	v_and_b32_e32 v115, 0xffff0000, v98
	v_and_b32_e32 v117, 0xffff0000, v100
	v_lshlrev_b32_e32 v114, 16, v98
	v_lshlrev_b32_e32 v116, 16, v100
	v_mul_f32_e32 v93, v115, v115
	v_mul_f32_e32 v113, v117, v117
	v_lshlrev_b32_e32 v98, 16, v99
	v_lshlrev_b32_e32 v100, 16, v101
	v_fmac_f32_e32 v93, v114, v114
	v_fmac_f32_e32 v113, v116, v116
	v_lshlrev_b32_e32 v70, 16, v75
	v_lshlrev_b32_e32 v68, 16, v76
	v_and_b32_e32 v79, 0xffff0000, v94
	v_and_b32_e32 v78, 0xffff0000, v96
	v_mul_f32_e32 v63, v69, v69
	v_fmac_f32_e32 v0, v72, v72
	v_and_b32_e32 v99, 0xffff0000, v99
	v_and_b32_e32 v101, 0xffff0000, v101
	v_fmac_f32_e32 v93, v98, v98
	v_fmac_f32_e32 v113, v100, v100
	v_and_b32_e32 v71, 0xffff0000, v75
	v_lshlrev_b32_e32 v66, 16, v77
	v_lshlrev_b32_e32 v75, 16, v94
	v_lshlrev_b32_e32 v74, 16, v96
	v_lshlrev_b32_e32 v76, 16, v97
	v_and_b32_e32 v80, 0xffff0000, v97
	v_pk_mul_f32 v[96:97], v[78:79], v[78:79]
	v_fmac_f32_e32 v63, v68, v68
	v_fmac_f32_e32 v0, v70, v70
	v_fmac_f32_e32 v93, v99, v99
	v_fmac_f32_e32 v113, v101, v101
	v_and_b32_e32 v67, 0xffff0000, v77
	v_lshlrev_b32_e32 v77, 16, v95
	v_pk_fma_f32 v[96:97], v[74:75], v[74:75], v[96:97]
	v_fmac_f32_e32 v63, v66, v66
	v_fmac_f32_e32 v0, v71, v71
	v_add_f32_e32 v93, v93, v113
	v_and_b32_e32 v81, 0xffff0000, v95
	v_pk_fma_f32 v[96:97], v[76:77], v[76:77], v[96:97]
	v_fmac_f32_e32 v63, v67, v67
	v_add_f32_e32 v0, v93, v0
	v_pk_fma_f32 v[96:97], v[80:81], v[80:81], v[96:97]
	v_add_f32_e32 v0, v63, v0
	v_add_f32_e32 v0, v0, v97
	v_add_f32_e32 v0, v96, v0
	v_and_b32_e32 v97, 0xffff0000, v42
	v_and_b32_e32 v96, 0xffff0000, v44
	v_lshlrev_b32_e32 v95, 16, v42
	v_lshlrev_b32_e32 v94, 16, v44
	v_lshlrev_b32_e32 v118, 16, v45
	v_and_b32_e32 v42, 0xffff0000, v45
	v_pk_mul_f32 v[44:45], v[96:97], v[96:97]
	v_lshlrev_b32_e32 v119, 16, v43
	v_pk_fma_f32 v[44:45], v[94:95], v[94:95], v[44:45]
	v_and_b32_e32 v43, 0xffff0000, v43
	v_pk_fma_f32 v[44:45], v[118:119], v[118:119], v[44:45]
	v_lshlrev_b32_e32 v110, 16, v34
	v_pk_fma_f32 v[44:45], v[42:43], v[42:43], v[44:45]
	v_and_b32_e32 v111, 0xffff0000, v34
	v_add_f32_e32 v0, v0, v45
	v_add_f32_e32 v0, v44, v0
	ds_bpermute_b32 v45, v82, v0
	v_lshlrev_b32_e32 v34, 16, v35
	v_and_b32_e32 v35, 0xffff0000, v35
	s_waitcnt vmcnt(9)
	v_pk_mul_f32 v[32:33], v[32:33], v[98:99]
	v_lshlrev_b32_e32 v112, 16, v36
	s_waitcnt lgkmcnt(0)
	v_add_f32_e32 v0, v0, v45
	ds_bpermute_b32 v63, v83, v0
	v_and_b32_e32 v113, 0xffff0000, v36
	v_pk_mul_f32 v[30:31], v[30:31], v[114:115]
	v_pk_mul_f32 v[26:27], v[26:27], v[116:117]
	v_lshlrev_b32_e32 v36, 16, v37
	s_waitcnt lgkmcnt(0)
	v_add_f32_e32 v0, v0, v63
	ds_bpermute_b32 v63, v84, v0
	v_and_b32_e32 v37, 0xffff0000, v37
	s_waitcnt vmcnt(2)
	v_lshlrev_b32_e32 v44, 16, v102
	v_and_b32_e32 v45, 0xffff0000, v102
	v_lshlrev_b32_e32 v102, 16, v103
	s_waitcnt lgkmcnt(0)
	v_add_f32_e32 v0, v0, v63
	ds_bpermute_b32 v63, v85, v0
	v_and_b32_e32 v103, 0xffff0000, v103
	v_lshlrev_b32_e32 v120, 16, v104
	v_and_b32_e32 v121, 0xffff0000, v104
	v_lshlrev_b32_e32 v104, 16, v105
	s_waitcnt lgkmcnt(0)
	v_add_f32_e32 v0, v0, v63
	ds_bpermute_b32 v63, v86, v0
	v_and_b32_e32 v105, 0xffff0000, v105
	s_waitcnt vmcnt(1)
	v_lshlrev_b32_e32 v122, 16, v106
	v_and_b32_e32 v123, 0xffff0000, v106
	v_lshlrev_b32_e32 v106, 16, v107
	s_waitcnt lgkmcnt(0)
	v_add_f32_e32 v0, v0, v63
	ds_bpermute_b32 v63, v87, v0
	v_and_b32_e32 v107, 0xffff0000, v107
	v_lshlrev_b32_e32 v124, 16, v108
	v_and_b32_e32 v125, 0xffff0000, v108
	v_lshlrev_b32_e32 v108, 16, v109
	s_waitcnt lgkmcnt(0)
	v_add_f32_e32 v0, v0, v63
	v_fmamk_f32 v0, v0, 0x3a000000, v223
	v_mul_f32_e32 v63, 0x4b800000, v0
	v_cmp_gt_f32_e64 s[36:37], s0, v0
	v_and_b32_e32 v109, 0xffff0000, v109
	s_waitcnt vmcnt(0)
; __device__ __forceinline__ size_t xoff(int row, int col) { return ((size_t)((row >> 8) * 32 + (col >> 6)) * 256 + (row & 255)) * 64 + (col & 63); }
; __device__ __forceinline__ u32x4 pack8(f32x4 v0, f32x4 v1) { u32x4 w; w.x = cvt_pk_bf16(v0[0], v0[1]); w.y = cvt_pk_bf16(v0[2], v0[3]); w.z = cvt_pk_bf16(v1[0], v1[1]); w.w = cvt_pk_bf16(v1[2], v1[3]); return w; }
; __device__ void norm_rows(const Params& p, int mode, float scale, const float* gpost) {
;     ...
;             for (int c = 0; c < 4; ++c) { xv[2 * c] += yv[2 * c] * gq[2 * c] * rs; xv[2 * c + 1] += yv[2 * c + 1] * gq[2 * c + 1] * rs; }
;         }
;         if (mode == 2) {
; #pragma unroll
;             for (int c = 0; c < 4; ++c) { *(f32x4*)(p.out + (size_t)row * DM + (c * 64 + lane) * 8) = xv[2 * c]; *(f32x4*)(p.out + (size_t)row * DM + (c * 64 + lane) * 8 + 4) = xv[2 * c + 1]; }
;         } else {
;             float ss = 0.f;
; #pragma unroll
;             for (int c = 0; c < 8; ++c) ss += xv[c][0] * xv[c][0] + xv[c][1] * xv[c][1] + xv[c][2] * xv[c][2] + xv[c][3] * xv[c][3];
;             ss = wave_sum(ss);
; #pragma unroll
;             for (int c = 0; c < 4; ++c) *(u32x4*)(X + xoff(row, (c * 64 + lane) * 8)) = pack8(xv[2 * c], xv[2 * c + 1]);
;             if (lane == 0) RS[row] = rsqrtf(ss * (1.0f / DM) + RMS_EPS);
	v_lshlrev_b32_e32 v126, 16, v38
	v_cndmask_b32_e64 v0, v0, v63, s[36:37]
	v_rsq_f32_e32 v0, v0
	v_and_b32_e32 v127, 0xffff0000, v38
	v_lshlrev_b32_e32 v38, 16, v39
	v_and_b32_e32 v39, 0xffff0000, v39
	v_mul_f32_e32 v63, 0x45800000, v0
	v_cndmask_b32_e64 v0, v0, v63, s[36:37]
	v_mul_f32_e32 v0, 0.5, v0
	v_pk_fma_f32 v[32:33], v[32:33], v[0:1], v[34:35] op_sel_hi:[1,0,1]
	v_mov_b32_e32 v34, v75
	v_mov_b32_e32 v35, v79
	v_pk_mul_f32 v[14:15], v[14:15], v[34:35]
	v_mov_b32_e32 v34, v77
	v_mov_b32_e32 v35, v81
	v_pk_mul_f32 v[16:17], v[16:17], v[34:35]
	v_mov_b32_e32 v34, v95
	v_mov_b32_e32 v35, v97
	v_mov_b32_e32 v75, v78
	v_mov_b32_e32 v77, v80
	v_pk_mul_f32 v[6:7], v[6:7], v[34:35]
	v_mov_b32_e32 v34, v119
	v_mov_b32_e32 v35, v43
	v_mov_b32_e32 v95, v96
	v_mov_b32_e32 v119, v42
	v_lshlrev_b32_e32 v128, 16, v40
	v_and_b32_e32 v129, 0xffff0000, v40
	v_lshlrev_b32_e32 v40, 16, v41
	v_and_b32_e32 v41, 0xffff0000, v41
	v_pk_fma_f32 v[30:31], v[30:31], v[0:1], v[110:111] op_sel_hi:[1,0,1]
	v_pk_mul_f32 v[28:29], v[28:29], v[100:101]
	v_pk_fma_f32 v[26:27], v[26:27], v[0:1], v[112:113] op_sel_hi:[1,0,1]
	v_pk_mul_f32 v[22:23], v[22:23], v[72:73]
	v_pk_mul_f32 v[24:25], v[24:25], v[70:71]
	v_pk_mul_f32 v[18:19], v[18:19], v[68:69]
	v_pk_mul_f32 v[20:21], v[20:21], v[66:67]
	v_pk_mul_f32 v[10:11], v[10:11], v[74:75]
	v_pk_mul_f32 v[12:13], v[12:13], v[76:77]
	v_pk_mul_f32 v[8:9], v[8:9], v[34:35]
	v_pk_mul_f32 v[2:3], v[2:3], v[94:95]
	v_pk_mul_f32 v[4:5], v[4:5], v[118:119]
	v_pk_fma_f32 v[28:29], v[28:29], v[0:1], v[36:37] op_sel_hi:[1,0,1]
	v_pk_fma_f32 v[24:25], v[24:25], v[0:1], v[102:103] op_sel_hi:[1,0,1]
	v_pk_fma_f32 v[22:23], v[22:23], v[0:1], v[44:45] op_sel_hi:[1,0,1]
	v_pk_fma_f32 v[20:21], v[20:21], v[0:1], v[104:105] op_sel_hi:[1,0,1]
	v_pk_fma_f32 v[18:19], v[18:19], v[0:1], v[120:121] op_sel_hi:[1,0,1]
	v_pk_fma_f32 v[16:17], v[16:17], v[0:1], v[106:107] op_sel_hi:[1,0,1]
	v_pk_fma_f32 v[14:15], v[14:15], v[0:1], v[122:123] op_sel_hi:[1,0,1]
	v_pk_fma_f32 v[12:13], v[12:13], v[0:1], v[108:109] op_sel_hi:[1,0,1]
	v_pk_fma_f32 v[10:11], v[10:11], v[0:1], v[124:125] op_sel_hi:[1,0,1]
	v_pk_fma_f32 v[8:9], v[8:9], v[0:1], v[38:39] op_sel_hi:[1,0,1]
	v_pk_fma_f32 v[34:35], v[6:7], v[0:1], v[126:127] op_sel_hi:[1,0,1]
	v_pk_fma_f32 v[36:37], v[4:5], v[0:1], v[40:41] op_sel_hi:[1,0,1]
	v_pk_fma_f32 v[38:39], v[2:3], v[0:1], v[128:129] op_sel_hi:[1,0,1]
	v_mul_f32_e32 v0, v31, v31
	v_mul_f32_e32 v2, v27, v27
	v_fmac_f32_e32 v0, v30, v30
	v_fmac_f32_e32 v2, v26, v26
	v_fmac_f32_e32 v0, v32, v32
	v_fmac_f32_e32 v2, v28, v28
	v_fmac_f32_e32 v0, v33, v33
	v_fmac_f32_e32 v2, v29, v29
	v_add_f32_e32 v0, v0, v2
	v_mul_f32_e32 v2, v23, v23
	v_fmac_f32_e32 v2, v22, v22
	v_fmac_f32_e32 v2, v24, v24
	v_fmac_f32_e32 v2, v25, v25
	v_add_f32_e32 v0, v2, v0
	v_mul_f32_e32 v2, v19, v19
	v_fmac_f32_e32 v2, v18, v18
	v_fmac_f32_e32 v2, v20, v20
	v_fmac_f32_e32 v2, v21, v21
	v_add_f32_e32 v0, v2, v0
	v_mul_f32_e32 v2, v15, v15
	v_fmac_f32_e32 v2, v14, v14
	v_fmac_f32_e32 v2, v16, v16
	v_fmac_f32_e32 v2, v17, v17
	v_add_f32_e32 v0, v2, v0
	v_mul_f32_e32 v2, v11, v11
	v_fmac_f32_e32 v2, v10, v10
	v_fmac_f32_e32 v2, v12, v12
	v_fmac_f32_e32 v2, v13, v13
	v_add_f32_e32 v0, v2, v0
	v_mul_f32_e32 v2, v35, v35
	v_fmac_f32_e32 v2, v34, v34
	v_fmac_f32_e32 v2, v8, v8
	v_fmac_f32_e32 v2, v9, v9
	v_add_f32_e32 v0, v2, v0
	v_mul_f32_e32 v2, v39, v39
	v_fmac_f32_e32 v2, v38, v38
	v_fmac_f32_e32 v2, v36, v36
	v_fmac_f32_e32 v2, v37, v37
	v_add_f32_e32 v0, v2, v0
	ds_bpermute_b32 v2, v82, v0
	v_cvt_pk_bf16_f32 v6, v26, v27
	v_cvt_pk_bf16_f32 v4, v30, v31
	v_cvt_pk_bf16_f32 v5, v32, v33
	v_cvt_pk_bf16_f32 v7, v28, v29
	s_waitcnt lgkmcnt(0)
	v_add_f32_e32 v0, v0, v2
	ds_bpermute_b32 v2, v83, v0
	v_lshrrev_b32_e32 v204, 6, v229
	v_mul_u32_u24_e32 v205, 0x1010, v204
	v_lshl_add_u32 v205, v228, 4, v205
	ds_write_b128 v205, v[4:7]
	s_waitcnt lgkmcnt(0)
	v_add_f32_e32 v0, v0, v2
	ds_bpermute_b32 v2, v84, v0
	v_cvt_pk_bf16_f32 v6, v18, v19
	v_or_b32_e32 v18, 8, v62
	v_ashrrev_i32_e32 v19, 31, v18
	v_lshlrev_b64 v[18:19], 15, v[18:19]
	s_waitcnt lgkmcnt(0)
	v_add_f32_e32 v0, v0, v2
	ds_bpermute_b32 v2, v85, v0
	v_lshl_add_u64 v[18:19], v[60:61], 0, v[18:19]
	v_cvt_pk_bf16_f32 v4, v22, v23
	v_cvt_pk_bf16_f32 v5, v24, v25
	v_cvt_pk_bf16_f32 v7, v20, v21
	s_waitcnt lgkmcnt(0)
	v_add_f32_e32 v0, v0, v2
	ds_bpermute_b32 v2, v86, v0
	ds_write_b128 v205, v[4:7] offset:1024
	s_waitcnt lgkmcnt(0)
	v_add_f32_e32 v0, v0, v2
	v_cvt_pk_bf16_f32 v6, v10, v11
	v_or_b32_e32 v10, 16, v62
	v_ashrrev_i32_e32 v11, 31, v10
	v_lshlrev_b64 v[10:11], 15, v[10:11]
	ds_bpermute_b32 v2, v87, v0
	v_cvt_pk_bf16_f32 v5, v16, v17
	v_lshl_add_u64 v[10:11], v[60:61], 0, v[10:11]
	v_cvt_pk_bf16_f32 v4, v14, v15
	v_cvt_pk_bf16_f32 v7, v12, v13
	ds_write_b128 v205, v[4:7] offset:2048
	s_nop 1
	v_cvt_pk_bf16_f32 v5, v8, v9
	v_or_b32_e32 v8, 24, v62
	v_ashrrev_i32_e32 v9, 31, v8
	v_lshlrev_b64 v[8:9], 15, v[8:9]
	v_lshl_add_u64 v[8:9], v[60:61], 0, v[8:9]
	v_cvt_pk_bf16_f32 v4, v34, v35
	v_cvt_pk_bf16_f32 v6, v38, v39
	v_cvt_pk_bf16_f32 v7, v36, v37
	ds_write_b128 v205, v[4:7] offset:3072
	v_readlane_b32 s2, v252, 6
	v_readlane_b32 s3, v252, 7
	v_lshrrev_b32_e32 v206, 3, v228
	v_mul_u32_u24_e32 v206, 0x1010, v206
	v_and_b32_e32 v207, 7, v228
	v_lshl_add_u32 v206, v204, 9, v206
	v_lshl_add_u32 v206, v207, 4, v206
	s_waitcnt lgkmcnt(0)
	s_barrier
	ds_read_b128 v[184:187], v206
	ds_read_b128 v[188:191], v206 offset:128
	ds_read_b128 v[196:199], v206 offset:256
	ds_read_b128 v[200:203], v206 offset:384
	v_lshrrev_b32_e32 v207, 8, v46
	v_lshlrev_b32_e32 v207, 5, v207
	v_lshl_add_u32 v207, v204, 2, v207
	v_lshlrev_b32_e32 v207, 15, v207
	v_and_b32_e32 v208, 0xf8, v46
	v_lshl_add_u32 v207, v208, 7, v207
	v_lshl_add_u32 v207, v228, 4, v207
	v_add_u32_e32 v208, 0x8000, v207
	v_add_u32_e32 v209, 0x10000, v207
	v_add_u32_e32 v210, 0x18000, v207
	s_waitcnt lgkmcnt(0)
	global_store_dwordx4 v207, v[184:187], s[2:3]
	global_store_dwordx4 v208, v[188:191], s[2:3]
	global_store_dwordx4 v209, v[196:199], s[2:3]
	global_store_dwordx4 v210, v[200:203], s[2:3]
	s_barrier
	s_and_saveexec_b64 s[0:1], vcc
	s_cbranch_execz .LBB0_786
	s_waitcnt lgkmcnt(0)
	v_add_f32_e32 v0, v0, v2
	v_fmamk_f32 v0, v0, 0x3a000000, v223
	s_mov_b32 s2, 0x800000
	v_mul_f32_e32 v2, 0x4b800000, v0
	v_cmp_gt_f32_e64 s[36:37], s2, v0
	v_readlane_b32 s2, v254, 22
	v_readlane_b32 s3, v254, 23
	v_cndmask_b32_e64 v0, v0, v2, s[36:37]
	v_rsq_f32_e32 v0, v0
	s_nop 0
	v_mul_f32_e32 v2, 0x45800000, v0
	v_cndmask_b32_e64 v0, v0, v2, s[36:37]
	v_lshl_add_u64 v[2:3], v[46:47], 2, s[2:3]
	global_store_dword v[2:3], v0, off
	s_branch .LBB0_786

; __device__ __forceinline__ size_t xoff(int row, int col) { return ((size_t)((row >> 8) * 32 + (col >> 6)) * 256 + (row & 255)) * 64 + (col & 63); }
; __device__ __forceinline__ void unpack8(u32x4 w, f32x4& v0, f32x4& v1) { v0 = (f32x4){bflo(w.x), bfhi(w.x), bflo(w.y), bfhi(w.y)}; v1 = (f32x4){bflo(w.z), bfhi(w.z), bflo(w.w), bfhi(w.w)}; }
; __device__ void norm_rows(const Params& p, int mode, float scale, const float* gpost) {
;     ...
;             f32x4 yv[8]; float ss = 0.f; u32x4 xw[4], yw[4]; f32x4 gq[8];
; #pragma unroll
;             for (int c = 0; c < 4; ++c) { xw[c] = *(const u32x4*)(X + xoff(row, (c * 64 + lane) * 8)); yw[c] = *(const u32x4*)(Y + (size_t)row * DM + (c * 64 + lane) * 8); }
; #pragma unroll
;             for (int c = 0; c < 4; ++c) { gq[2 * c] = *(const f32x4*)(gpost + (c * 64 + lane) * 8); gq[2 * c + 1] = *(const f32x4*)(gpost + (c * 64 + lane) * 8 + 4); }
;             asm volatile("" ::: "memory");
; #pragma unroll
;             for (int c = 0; c < 4; ++c) { unpack8(xw[c], xv[2 * c], xv[2 * c + 1]); unpack8(yw[c], yv[2 * c], yv[2 * c + 1]); }
; #pragma unroll
;             for (int c = 0; c < 8; ++c) ss += yv[c][0] * yv[c][0] + yv[c][1] * yv[c][1] + yv[c][2] * yv[c][2] + yv[c][3] * yv[c][3];
;             ss = wave_sum(ss);
;             const float rs = rsqrtf(ss * (1.0f / DM) + RMS_EPS) * scale;
.LBB0_1013:
	v_ashrrev_i32_e32 v47, 31, v46
	v_lshlrev_b64 v[2:3], 12, v[46:47]
	v_lshl_add_u64 v[2:3], v[58:59], 0, v[2:3]
	global_load_dwordx4 v[80:83], v[2:3], off offset:1024
	global_load_dwordx4 v[86:89], v[2:3], off offset:2048
	v_ashrrev_i32_e32 v0, 3, v46
	v_and_b32_e32 v39, 0xffffffe0, v0
	v_and_b32_e32 v4, 0x3fc0, v100
	v_or_b32_e32 v68, v39, v96
	v_lshlrev_b32_e32 v0, 1, v4
	v_ashrrev_i32_e32 v69, 31, v68
	v_lshl_add_u64 v[66:67], v[48:49], 0, v[0:1]
	v_lshlrev_b64 v[4:5], 15, v[68:69]
	v_lshl_add_u64 v[70:71], v[66:67], 0, v[4:5]
	global_load_dwordx4 v[42:45], v[2:3], off offset:3072
	s_waitcnt lgkmcnt(0)
	global_load_dwordx4 v[34:37], v[70:71], off
	global_load_dwordx4 v[102:105], v[2:3], off
	global_load_dwordx4 v[30:33], v[50:51], off offset:16
	global_load_dwordx4 v[22:25], v[50:51], off
	global_load_dwordx4 v[18:21], v[52:53], off offset:16
	global_load_dwordx4 v[26:29], v[52:53], off
	global_load_dwordx4 v[10:13], v[54:55], off offset:16
	global_load_dwordx4 v[14:17], v[54:55], off
	global_load_dwordx4 v[2:5], v[56:57], off offset:16
	global_load_dwordx4 v[6:9], v[56:57], off
	v_or_b32_e32 v38, v39, v97
	v_or_b32_e32 v40, v39, v98
	v_or_b32_e32 v72, v39, v99
	v_ashrrev_i32_e32 v39, 31, v38
	v_lshlrev_b64 v[38:39], 15, v[38:39]
	v_ashrrev_i32_e32 v41, 31, v40
	v_ashrrev_i32_e32 v73, 31, v72
	v_lshl_add_u64 v[38:39], v[66:67], 0, v[38:39]
	global_load_dwordx4 v[106:109], v[38:39], off
	v_lshlrev_b64 v[38:39], 15, v[40:41]
	v_lshlrev_b64 v[40:41], 15, v[72:73]
	v_lshl_add_u64 v[38:39], v[66:67], 0, v[38:39]
	v_lshl_add_u64 v[40:41], v[66:67], 0, v[40:41]
	global_load_dwordx4 v[110:113], v[38:39], off
	s_nop 0
	global_load_dwordx4 v[38:41], v[40:41], off
	s_mov_b32 s0, 0x800000
	s_waitcnt vmcnt(15)
	v_and_b32_e32 v79, 0xffff0000, v80
	v_lshlrev_b32_e32 v78, 16, v80
	v_and_b32_e32 v75, 0xffff0000, v82
	v_mul_f32_e32 v0, v79, v79
	s_waitcnt vmcnt(11)
	v_and_b32_e32 v121, 0xffff0000, v102
	v_and_b32_e32 v123, 0xffff0000, v104
	v_lshlrev_b32_e32 v120, 16, v102
	v_lshlrev_b32_e32 v122, 16, v104
	v_mul_f32_e32 v63, v121, v121
	v_mul_f32_e32 v65, v123, v123
	v_lshlrev_b32_e32 v102, 16, v103
	v_lshlrev_b32_e32 v104, 16, v105
	v_fmac_f32_e32 v63, v120, v120
	v_fmac_f32_e32 v65, v122, v122
	v_lshlrev_b32_e32 v76, 16, v81
	v_lshlrev_b32_e32 v74, 16, v82
	v_and_b32_e32 v85, 0xffff0000, v86
	v_and_b32_e32 v84, 0xffff0000, v88
	v_mul_f32_e32 v61, v75, v75
	v_fmac_f32_e32 v0, v78, v78
	v_and_b32_e32 v103, 0xffff0000, v103
	v_and_b32_e32 v105, 0xffff0000, v105
	v_fmac_f32_e32 v63, v102, v102
	v_fmac_f32_e32 v65, v104, v104
	v_and_b32_e32 v77, 0xffff0000, v81
	v_lshlrev_b32_e32 v72, 16, v83
	v_lshlrev_b32_e32 v81, 16, v86
	v_lshlrev_b32_e32 v80, 16, v88
	v_pk_mul_f32 v[114:115], v[84:85], v[84:85]
	v_fmac_f32_e32 v61, v74, v74
	v_fmac_f32_e32 v0, v76, v76
	v_fmac_f32_e32 v63, v103, v103
	v_fmac_f32_e32 v65, v105, v105
	v_and_b32_e32 v73, 0xffff0000, v83
	v_lshlrev_b32_e32 v83, 16, v87
	v_lshlrev_b32_e32 v82, 16, v89
	v_pk_fma_f32 v[114:115], v[80:81], v[80:81], v[114:115]
	v_fmac_f32_e32 v61, v72, v72
	v_fmac_f32_e32 v0, v77, v77
	v_add_f32_e32 v63, v63, v65
	v_and_b32_e32 v87, 0xffff0000, v87
	v_and_b32_e32 v86, 0xffff0000, v89
	v_pk_fma_f32 v[114:115], v[82:83], v[82:83], v[114:115]
	v_fmac_f32_e32 v61, v73, v73
	v_add_f32_e32 v0, v63, v0
	v_pk_fma_f32 v[114:115], v[86:87], v[86:87], v[114:115]
	v_add_f32_e32 v0, v61, v0
	v_add_f32_e32 v0, v0, v115
	v_add_f32_e32 v0, v114, v0
	v_and_b32_e32 v115, 0xffff0000, v42
	v_and_b32_e32 v114, 0xffff0000, v44
	v_lshlrev_b32_e32 v89, 16, v42
	v_lshlrev_b32_e32 v88, 16, v44
	v_lshlrev_b32_e32 v124, 16, v45
	v_and_b32_e32 v42, 0xffff0000, v45
	v_pk_mul_f32 v[44:45], v[114:115], v[114:115]
	v_lshlrev_b32_e32 v125, 16, v43
	v_pk_fma_f32 v[44:45], v[88:89], v[88:89], v[44:45]
	v_and_b32_e32 v43, 0xffff0000, v43
	v_pk_fma_f32 v[44:45], v[124:125], v[124:125], v[44:45]
	v_lshlrev_b32_e32 v116, 16, v34
	v_pk_fma_f32 v[44:45], v[42:43], v[42:43], v[44:45]
	v_and_b32_e32 v117, 0xffff0000, v34
	v_add_f32_e32 v0, v0, v45
	v_add_f32_e32 v0, v44, v0
	ds_bpermute_b32 v45, v90, v0
	v_lshlrev_b32_e32 v34, 16, v35
	v_and_b32_e32 v35, 0xffff0000, v35
	s_waitcnt vmcnt(9)
	v_pk_mul_f32 v[24:25], v[24:25], v[102:103]
	v_lshlrev_b32_e32 v118, 16, v36
	s_waitcnt lgkmcnt(0)
	v_add_f32_e32 v0, v0, v45
	ds_bpermute_b32 v61, v91, v0
	v_and_b32_e32 v119, 0xffff0000, v36
	v_lshlrev_b32_e32 v36, 16, v37
	v_and_b32_e32 v37, 0xffff0000, v37
	s_waitcnt vmcnt(2)
	v_lshlrev_b32_e32 v44, 16, v106
	s_waitcnt lgkmcnt(0)
	v_add_f32_e32 v0, v0, v61
	ds_bpermute_b32 v61, v92, v0
	v_and_b32_e32 v45, 0xffff0000, v106
	v_lshlrev_b32_e32 v106, 16, v107
	v_and_b32_e32 v107, 0xffff0000, v107
	v_lshlrev_b32_e32 v126, 16, v108
	s_waitcnt lgkmcnt(0)
	v_add_f32_e32 v0, v0, v61
	ds_bpermute_b32 v61, v93, v0
	v_and_b32_e32 v127, 0xffff0000, v108
	v_lshlrev_b32_e32 v108, 16, v109
	v_and_b32_e32 v109, 0xffff0000, v109
	s_waitcnt vmcnt(1)
	v_lshlrev_b32_e32 v128, 16, v110
	s_waitcnt lgkmcnt(0)
	v_add_f32_e32 v0, v0, v61
	ds_bpermute_b32 v61, v94, v0
	v_and_b32_e32 v129, 0xffff0000, v110
	v_lshlrev_b32_e32 v110, 16, v111
	v_and_b32_e32 v111, 0xffff0000, v111
	v_lshlrev_b32_e32 v130, 16, v112
	s_waitcnt lgkmcnt(0)
	v_add_f32_e32 v0, v0, v61
	ds_bpermute_b32 v61, v95, v0
	v_and_b32_e32 v131, 0xffff0000, v112
	v_lshlrev_b32_e32 v112, 16, v113
	v_and_b32_e32 v113, 0xffff0000, v113
	s_waitcnt vmcnt(0)
	v_lshlrev_b32_e32 v132, 16, v38
	s_waitcnt lgkmcnt(0)
; __device__ __forceinline__ size_t xoff(int row, int col) { return ((size_t)((row >> 8) * 32 + (col >> 6)) * 256 + (row & 255)) * 64 + (col & 63); }
; __device__ __forceinline__ u32x4 pack8(f32x4 v0, f32x4 v1) { u32x4 w; w.x = cvt_pk_bf16(v0[0], v0[1]); w.y = cvt_pk_bf16(v0[2], v0[3]); w.z = cvt_pk_bf16(v1[0], v1[1]); w.w = cvt_pk_bf16(v1[2], v1[3]); return w; }
; __device__ void norm_rows(const Params& p, int mode, float scale, const float* gpost) {
;     ...
;             const float rs = rsqrtf(ss * (1.0f / DM) + RMS_EPS) * scale;
; #pragma unroll
;             for (int c = 0; c < 4; ++c) { xv[2 * c] += yv[2 * c] * gq[2 * c] * rs; xv[2 * c + 1] += yv[2 * c + 1] * gq[2 * c + 1] * rs; }
;         }
;         if (mode == 2) {
; #pragma unroll
;             for (int c = 0; c < 4; ++c) { *(f32x4*)(p.out + (size_t)row * DM + (c * 64 + lane) * 8) = xv[2 * c]; *(f32x4*)(p.out + (size_t)row * DM + (c * 64 + lane) * 8 + 4) = xv[2 * c + 1]; }
;         } else {
;             float ss = 0.f;
; #pragma unroll
;             for (int c = 0; c < 8; ++c) ss += xv[c][0] * xv[c][0] + xv[c][1] * xv[c][1] + xv[c][2] * xv[c][2] + xv[c][3] * xv[c][3];
;             ss = wave_sum(ss);
; #pragma unroll
;             for (int c = 0; c < 4; ++c) *(u32x4*)(X + xoff(row, (c * 64 + lane) * 8)) = pack8(xv[2 * c], xv[2 * c + 1]);
;             if (lane == 0) RS[row] = rsqrtf(ss * (1.0f / DM) + RMS_EPS);
	v_add_f32_e32 v0, v0, v61
	v_fmamk_f32 v0, v0, 0x3a000000, v223
	v_mul_f32_e32 v61, 0x4b800000, v0
	v_cmp_gt_f32_e32 vcc, s0, v0
	v_and_b32_e32 v133, 0xffff0000, v38
	v_lshlrev_b32_e32 v38, 16, v39
	v_cndmask_b32_e32 v0, v0, v61, vcc
	v_rsq_f32_e32 v0, v0
	v_and_b32_e32 v39, 0xffff0000, v39
	v_lshlrev_b32_e32 v134, 16, v40
	v_and_b32_e32 v135, 0xffff0000, v40
	v_mul_f32_e32 v61, 0x45800000, v0
	v_cndmask_b32_e32 v0, v0, v61, vcc
	v_mul_f32_e32 v0, 0.5, v0
	v_pk_fma_f32 v[24:25], v[24:25], v[0:1], v[34:35] op_sel_hi:[1,0,1]
	v_mov_b32_e32 v34, v81
	v_mov_b32_e32 v35, v85
	v_pk_mul_f32 v[14:15], v[14:15], v[34:35]
	v_mov_b32_e32 v34, v83
	v_mov_b32_e32 v35, v87
	v_pk_mul_f32 v[16:17], v[16:17], v[34:35]
	v_mov_b32_e32 v34, v89
	v_mov_b32_e32 v35, v115
	v_mov_b32_e32 v81, v84
	v_mov_b32_e32 v83, v86
	v_pk_mul_f32 v[6:7], v[6:7], v[34:35]
	v_mov_b32_e32 v34, v125
	v_mov_b32_e32 v35, v43
	v_mov_b32_e32 v89, v114
	v_mov_b32_e32 v125, v42
	v_lshlrev_b32_e32 v40, 16, v41
	v_and_b32_e32 v41, 0xffff0000, v41
	v_pk_mul_f32 v[22:23], v[22:23], v[120:121]
	v_pk_mul_f32 v[30:31], v[30:31], v[122:123]
	v_pk_mul_f32 v[32:33], v[32:33], v[104:105]
	v_pk_mul_f32 v[26:27], v[26:27], v[78:79]
	v_pk_mul_f32 v[28:29], v[28:29], v[76:77]
	v_pk_mul_f32 v[18:19], v[18:19], v[74:75]
	v_pk_mul_f32 v[20:21], v[20:21], v[72:73]
	v_pk_mul_f32 v[10:11], v[10:11], v[80:81]
	v_pk_mul_f32 v[12:13], v[12:13], v[82:83]
	v_pk_mul_f32 v[8:9], v[8:9], v[34:35]
	v_pk_mul_f32 v[2:3], v[2:3], v[88:89]
	v_pk_mul_f32 v[4:5], v[4:5], v[124:125]
	v_pk_fma_f32 v[22:23], v[22:23], v[0:1], v[116:117] op_sel_hi:[1,0,1]
	v_pk_fma_f32 v[32:33], v[32:33], v[0:1], v[36:37] op_sel_hi:[1,0,1]
	v_pk_fma_f32 v[30:31], v[30:31], v[0:1], v[118:119] op_sel_hi:[1,0,1]
	v_pk_fma_f32 v[28:29], v[28:29], v[0:1], v[106:107] op_sel_hi:[1,0,1]
	v_pk_fma_f32 v[26:27], v[26:27], v[0:1], v[44:45] op_sel_hi:[1,0,1]
	v_pk_fma_f32 v[20:21], v[20:21], v[0:1], v[108:109] op_sel_hi:[1,0,1]
	v_pk_fma_f32 v[18:19], v[18:19], v[0:1], v[126:127] op_sel_hi:[1,0,1]
	v_pk_fma_f32 v[16:17], v[16:17], v[0:1], v[110:111] op_sel_hi:[1,0,1]
	v_pk_fma_f32 v[14:15], v[14:15], v[0:1], v[128:129] op_sel_hi:[1,0,1]
	v_pk_fma_f32 v[12:13], v[12:13], v[0:1], v[112:113] op_sel_hi:[1,0,1]
	v_pk_fma_f32 v[10:11], v[10:11], v[0:1], v[130:131] op_sel_hi:[1,0,1]
	v_pk_fma_f32 v[8:9], v[8:9], v[0:1], v[38:39] op_sel_hi:[1,0,1]
	v_pk_fma_f32 v[6:7], v[6:7], v[0:1], v[132:133] op_sel_hi:[1,0,1]
	v_pk_fma_f32 v[4:5], v[4:5], v[0:1], v[40:41] op_sel_hi:[1,0,1]
	v_pk_fma_f32 v[2:3], v[2:3], v[0:1], v[134:135] op_sel_hi:[1,0,1]
	s_andn2_b64 vcc, exec, s[22:23]
	s_mov_b64 s[0:1], -1
	s_cbranch_vccnz .LBB0_1017
	v_mul_f32_e32 v0, v23, v23
	v_mul_f32_e32 v34, v31, v31
	v_fmac_f32_e32 v0, v22, v22
	v_fmac_f32_e32 v34, v30, v30
	v_fmac_f32_e32 v0, v24, v24
	v_fmac_f32_e32 v34, v32, v32
	v_fmac_f32_e32 v0, v25, v25
	v_fmac_f32_e32 v34, v33, v33
	v_add_f32_e32 v0, v0, v34
	v_mul_f32_e32 v34, v27, v27
	v_fmac_f32_e32 v34, v26, v26
	v_fmac_f32_e32 v34, v28, v28
	v_fmac_f32_e32 v34, v29, v29
	v_add_f32_e32 v0, v34, v0
	v_mul_f32_e32 v34, v19, v19
	v_fmac_f32_e32 v34, v18, v18
	v_fmac_f32_e32 v34, v20, v20
	v_fmac_f32_e32 v34, v21, v21
	v_add_f32_e32 v0, v34, v0
	v_mul_f32_e32 v34, v15, v15
	v_fmac_f32_e32 v34, v14, v14
	v_fmac_f32_e32 v34, v16, v16
	v_fmac_f32_e32 v34, v17, v17
	v_add_f32_e32 v0, v34, v0
	v_mul_f32_e32 v34, v11, v11
	v_fmac_f32_e32 v34, v10, v10
	v_fmac_f32_e32 v34, v12, v12
	v_fmac_f32_e32 v34, v13, v13
	v_add_f32_e32 v0, v34, v0
	v_mul_f32_e32 v34, v7, v7
	v_fmac_f32_e32 v34, v6, v6
	v_fmac_f32_e32 v34, v8, v8
	v_fmac_f32_e32 v34, v9, v9
	v_add_f32_e32 v0, v34, v0
	v_mul_f32_e32 v34, v3, v3
	v_fmac_f32_e32 v34, v2, v2
	v_fmac_f32_e32 v34, v4, v4
	v_fmac_f32_e32 v34, v5, v5
	v_add_f32_e32 v0, v34, v0
	ds_bpermute_b32 v34, v90, v0
	v_or_b32_e32 v40, 8, v68
	v_ashrrev_i32_e32 v41, 31, v40
	v_lshlrev_b64 v[40:41], 15, v[40:41]
	v_cvt_pk_bf16_f32 v36, v22, v23
	s_waitcnt lgkmcnt(0)
	v_add_f32_e32 v0, v0, v34
	ds_bpermute_b32 v34, v91, v0
	v_cvt_pk_bf16_f32 v37, v24, v25
	v_cvt_pk_bf16_f32 v38, v30, v31
	v_cvt_pk_bf16_f32 v39, v32, v33
	v_lshl_add_u64 v[40:41], v[66:67], 0, v[40:41]
	s_waitcnt lgkmcnt(0)
	v_add_f32_e32 v0, v0, v34
	ds_bpermute_b32 v34, v92, v0
	v_lshrrev_b32_e32 v204, 6, v229
	v_mul_u32_u24_e32 v205, 0x1010, v204
	v_lshl_add_u32 v205, v228, 4, v205
	ds_write_b128 v205, v[36:39]
	s_waitcnt lgkmcnt(0)
	v_add_f32_e32 v0, v0, v34
	ds_bpermute_b32 v34, v93, v0
	v_cvt_pk_bf16_f32 v36, v26, v27
	v_cvt_pk_bf16_f32 v37, v28, v29
	v_cvt_pk_bf16_f32 v38, v18, v19
	v_cvt_pk_bf16_f32 v39, v20, v21
	s_waitcnt lgkmcnt(0)
	v_add_f32_e32 v0, v0, v34
	ds_bpermute_b32 v34, v94, v0
	ds_write_b128 v205, v[36:39] offset:1024
	v_or_b32_e32 v40, 16, v68
	v_ashrrev_i32_e32 v41, 31, v40
	v_lshlrev_b64 v[40:41], 15, v[40:41]
	s_waitcnt lgkmcnt(0)
	v_add_f32_e32 v0, v0, v34
	ds_bpermute_b32 v34, v95, v0
	v_lshl_add_u64 v[40:41], v[66:67], 0, v[40:41]
	v_cvt_pk_bf16_f32 v36, v14, v15
	v_cvt_pk_bf16_f32 v37, v16, v17
	v_cvt_pk_bf16_f32 v38, v10, v11
	v_cvt_pk_bf16_f32 v39, v12, v13
	ds_write_b128 v205, v[36:39] offset:2048
	v_or_b32_e32 v40, 24, v68
	v_ashrrev_i32_e32 v41, 31, v40
	v_lshlrev_b64 v[40:41], 15, v[40:41]
	v_lshl_add_u64 v[40:41], v[66:67], 0, v[40:41]
	v_cvt_pk_bf16_f32 v36, v6, v7
	v_cvt_pk_bf16_f32 v37, v8, v9
	v_cvt_pk_bf16_f32 v38, v2, v3
	v_cvt_pk_bf16_f32 v39, v4, v5
	ds_write_b128 v205, v[36:39] offset:3072
	v_readlane_b32 s2, v252, 6
	v_readlane_b32 s3, v252, 7
	v_lshrrev_b32_e32 v206, 3, v228
	v_mul_u32_u24_e32 v206, 0x1010, v206
	v_and_b32_e32 v207, 7, v228
	v_lshl_add_u32 v206, v204, 9, v206
	v_lshl_add_u32 v206, v207, 4, v206
	s_waitcnt lgkmcnt(0)
	s_barrier
	ds_read_b128 v[184:187], v206
	ds_read_b128 v[188:191], v206 offset:128
	ds_read_b128 v[196:199], v206 offset:256
	ds_read_b128 v[200:203], v206 offset:384
	v_lshrrev_b32_e32 v207, 8, v46
	v_lshlrev_b32_e32 v207, 5, v207
	v_lshl_add_u32 v207, v204, 2, v207
	v_lshlrev_b32_e32 v207, 15, v207
	v_and_b32_e32 v208, 0xf8, v46
	v_lshl_add_u32 v207, v208, 7, v207
	v_lshl_add_u32 v207, v228, 4, v207
	v_add_u32_e32 v208, 0x8000, v207
	v_add_u32_e32 v209, 0x10000, v207
	v_add_u32_e32 v210, 0x18000, v207
	s_waitcnt lgkmcnt(0)
	global_store_dwordx4 v207, v[184:187], s[2:3]
	global_store_dwordx4 v208, v[188:191], s[2:3]
	global_store_dwordx4 v209, v[196:199], s[2:3]
	global_store_dwordx4 v210, v[200:203], s[2:3]
	s_barrier
	s_and_saveexec_b64 s[0:1], s[36:37]
	s_cbranch_execz .LBB0_1016
	s_waitcnt lgkmcnt(0)
	v_add_f32_e32 v0, v0, v34
	v_fmamk_f32 v0, v0, 0x3a000000, v223
	s_mov_b32 s2, 0x800000
	v_mul_f32_e32 v34, 0x4b800000, v0
	v_cmp_gt_f32_e32 vcc, s2, v0
	v_readlane_b32 s2, v254, 22
	v_readlane_b32 s3, v254, 23
	v_cndmask_b32_e32 v0, v0, v34, vcc
	v_rsq_f32_e32 v0, v0
	s_nop 0
	v_mul_f32_e32 v34, 0x45800000, v0
	v_cndmask_b32_e32 v0, v0, v34, vcc
	v_lshl_add_u64 v[34:35], v[46:47], 2, s[2:3]
	global_store_dword v[34:35], v0, off
